# v16 plus: compiler-inserted mid-load-segment lgkmcnt(0) waits removed in the three TailOrder GEMM K-loops
# baseline (speedup 1.0000x reference)
; #define PG8_STAGE(bufoff, gbase, voff) do { _Pragma("unroll") for (int _i = 0; _i < 2; ++_i) \
;         __builtin_amdgcn_global_load_lds((const unsigned*)((const char*)(gbase) + (voff)[_i]), (PG8_LAS unsigned*)(lds + (bufoff) + ldsw + _i * 8192), 16, 0, 0); } while (0)
; #define PG8_LDA(dst, b, h) do { _Pragma("unroll") for (int m = 0; m < 4; ++m) _Pragma("unroll") for (int k = 0; k < 2; ++k) dst[m][k] = *(const PG8_LAS bf16x8*)(lds + PG8_SA(b, h) + aoff + m * 2048 + k * 1024); } while (0)
; #define PG8_LDB(dst, b, h) do { _Pragma("unroll") for (int n = 0; n < 2; ++n) _Pragma("unroll") for (int k = 0; k < 2; ++k) dst[n][k] = *(const PG8_LAS bf16x8*)(lds + PG8_SB(b, h) + boff + n * 2048 + k * 1024); } while (0)
; #define PG8_MMA(ai, bj, At, Bt) do { __builtin_amdgcn_s_setprio(1); _Pragma("unroll") for (int m = 0; m < 4; ++m) _Pragma("unroll") for (int n = 0; n < 2; ++n) _Pragma("unroll") for (int k = 0; k < 2; ++k) \
;         acc[ai][bj][m][n] = __builtin_amdgcn_mfma_f32_16x16x32_bf16(Bt[n][k], At[m][k], acc[ai][bj][m][n], 0, 0, 0); __builtin_amdgcn_s_setprio(0); } while (0)
; #define PG8_WAIT_V(n) asm volatile("s_waitcnt vmcnt(" #n ")" ::: "memory")
; #define PG8_WAIT_L(n) asm volatile("s_waitcnt lgkmcnt(" #n ")" ::: "memory")
; #define PG8_BAR __builtin_amdgcn_s_barrier()
; #define PG8_SCHED __builtin_amdgcn_sched_barrier(0)
; template <class Epi, class Sched, bool ALIGN_EPI = false, bool SP2 = false>
; __device__ __forceinline__ void gemm_phase(PG8_LAS unsigned char* lds, const Gemm g, const Sched& S, const Epi& E) {
;     ...
;             PG8_LDB(B0, 1, 0); PG8_LDB(B1, 1, 1); PG8_SCHED; PG8_LDA(At, 1, 0); PG8_STAGE(PG8_SA(0, 1), a2 + hstep, voffA);
;             PG8_WAIT_V(8); PG8_WAIT_L(0); PG8_BAR; PG8_MMA(0, 0, At, B0); if (doB1) PG8_MMA(0, 1, At, B1); PG8_BAR; PG8_SCHED;
.LBB0_371:
	s_barrier
	v_add_u32_e32 v128, 0x18000, v228
	ds_read_b128 v[154:157], v128
	ds_read_b128 v[158:161], v128 offset:1024
	ds_read_b128 v[162:165], v128 offset:2048
	ds_read_b128 v[166:169], v128 offset:3072
	v_add_u32_e32 v128, 0x1c000, v228
	ds_read_b128 v[130:133], v128
	ds_read_b128 v[134:137], v128 offset:1024
	ds_read_b128 v[146:149], v128 offset:2048
	ds_read_b128 v[150:153], v128 offset:3072
	s_add_u32 s94, s94, 0x40000
	s_addc_u32 s95, s95, 0
	s_mov_b32 m0, s27
	s_nop 0
	v_lshl_add_u64 v[138:139], s[94:95], 0, v[202:203]
	ds_read_b128 v[194:197], v229 offset:32768
	ds_read_b128 v[198:201], v229 offset:33792
	ds_read_b128 v[186:189], v229 offset:34816
	ds_read_b128 v[190:193], v229 offset:35840
	ds_read_b128 v[178:181], v229 offset:36864
	ds_read_b128 v[182:185], v229 offset:37888
	ds_read_b128 v[170:173], v229 offset:38912
	ds_read_b128 v[174:177], v229 offset:39936
	global_load_lds_dwordx4 v[138:139], off
	v_lshl_add_u64 v[138:139], s[94:95], 0, v[206:207]
	s_mov_b32 m0, s28
	s_nop 0
	global_load_lds_dwordx4 v[138:139], off
	s_waitcnt vmcnt(8)
	s_waitcnt lgkmcnt(0)
	s_barrier
	s_setprio 1
	s_waitcnt lgkmcnt(0)
	v_mfma_f32_16x16x32_bf16 v[112:115], v[154:157], v[194:197], v[112:115]
	v_mfma_f32_16x16x32_bf16 v[142:145], v[158:161], v[198:201], v[112:115]
	v_mfma_f32_16x16x32_bf16 v[112:115], v[162:165], v[194:197], v[116:119]
	v_mfma_f32_16x16x32_bf16 v[138:141], v[166:169], v[198:201], v[112:115]
	v_mfma_f32_16x16x32_bf16 v[112:115], v[154:157], v[186:189], v[124:127]
	v_mfma_f32_16x16x32_bf16 v[124:127], v[158:161], v[190:193], v[112:115]
	v_mfma_f32_16x16x32_bf16 v[112:115], v[162:165], v[186:189], v[120:123]
	v_mfma_f32_16x16x32_bf16 v[108:111], v[154:157], v[178:181], v[108:111]
	v_mfma_f32_16x16x32_bf16 v[104:107], v[162:165], v[178:181], v[104:107]
	v_mfma_f32_16x16x32_bf16 v[100:103], v[154:157], v[170:173], v[100:103]
	v_mfma_f32_16x16x32_bf16 v[96:99], v[162:165], v[170:173], v[96:99]
	v_mfma_f32_16x16x32_bf16 v[120:123], v[166:169], v[190:193], v[112:115]
	v_mfma_f32_16x16x32_bf16 v[108:111], v[158:161], v[182:185], v[108:111]
	v_mfma_f32_16x16x32_bf16 v[104:107], v[166:169], v[182:185], v[104:107]
	v_mfma_f32_16x16x32_bf16 v[100:103], v[158:161], v[174:177], v[100:103]
	v_mfma_f32_16x16x32_bf16 v[96:99], v[166:169], v[174:177], v[96:99]
	s_setprio 0
	s_and_b64 vcc, exec, s[6:7]
	s_cbranch_vccnz .LBB0_373
	s_setprio 1
	v_mfma_f32_16x16x32_bf16 v[92:95], v[130:133], v[194:197], v[92:95]
	v_mfma_f32_16x16x32_bf16 v[88:91], v[146:149], v[194:197], v[88:91]
	v_mfma_f32_16x16x32_bf16 v[84:87], v[130:133], v[186:189], v[84:87]
	v_mfma_f32_16x16x32_bf16 v[80:83], v[146:149], v[186:189], v[80:83]
	v_mfma_f32_16x16x32_bf16 v[76:79], v[130:133], v[178:181], v[76:79]
	v_mfma_f32_16x16x32_bf16 v[72:75], v[146:149], v[178:181], v[72:75]
	v_mfma_f32_16x16x32_bf16 v[68:71], v[130:133], v[170:173], v[68:71]
	v_mfma_f32_16x16x32_bf16 v[64:67], v[146:149], v[170:173], v[64:67]
	v_mfma_f32_16x16x32_bf16 v[92:95], v[134:137], v[198:201], v[92:95]
	v_mfma_f32_16x16x32_bf16 v[88:91], v[150:153], v[198:201], v[88:91]
	v_mfma_f32_16x16x32_bf16 v[84:87], v[134:137], v[190:193], v[84:87]
	v_mfma_f32_16x16x32_bf16 v[80:83], v[150:153], v[190:193], v[80:83]
	v_mfma_f32_16x16x32_bf16 v[76:79], v[134:137], v[182:185], v[76:79]
	v_mfma_f32_16x16x32_bf16 v[72:75], v[150:153], v[182:185], v[72:75]
	v_mfma_f32_16x16x32_bf16 v[68:71], v[134:137], v[174:177], v[68:71]
	v_mfma_f32_16x16x32_bf16 v[64:67], v[150:153], v[174:177], v[64:67]
	s_setprio 0

; #define PG8_STAGE(bufoff, gbase, voff) do { _Pragma("unroll") for (int _i = 0; _i < 2; ++_i) \
;         __builtin_amdgcn_global_load_lds((const unsigned*)((const char*)(gbase) + (voff)[_i]), (PG8_LAS unsigned*)(lds + (bufoff) + ldsw + _i * 8192), 16, 0, 0); } while (0)
; #define PG8_LDA(dst, b, h) do { _Pragma("unroll") for (int m = 0; m < 4; ++m) _Pragma("unroll") for (int k = 0; k < 2; ++k) dst[m][k] = *(const PG8_LAS bf16x8*)(lds + PG8_SA(b, h) + aoff + m * 2048 + k * 1024); } while (0)
; #define PG8_LDB(dst, b, h) do { _Pragma("unroll") for (int n = 0; n < 2; ++n) _Pragma("unroll") for (int k = 0; k < 2; ++k) dst[n][k] = *(const PG8_LAS bf16x8*)(lds + PG8_SB(b, h) + boff + n * 2048 + k * 1024); } while (0)
; #define PG8_MMA(ai, bj, At, Bt) do { __builtin_amdgcn_s_setprio(1); _Pragma("unroll") for (int m = 0; m < 4; ++m) _Pragma("unroll") for (int n = 0; n < 2; ++n) _Pragma("unroll") for (int k = 0; k < 2; ++k) \
;         acc[ai][bj][m][n] = __builtin_amdgcn_mfma_f32_16x16x32_bf16(Bt[n][k], At[m][k], acc[ai][bj][m][n], 0, 0, 0); __builtin_amdgcn_s_setprio(0); } while (0)
; #define PG8_WAIT_V(n) asm volatile("s_waitcnt vmcnt(" #n ")" ::: "memory")
; #define PG8_WAIT_L(n) asm volatile("s_waitcnt lgkmcnt(" #n ")" ::: "memory")
; #define PG8_BAR __builtin_amdgcn_s_barrier()
; #define PG8_SCHED __builtin_amdgcn_sched_barrier(0)
; template <class Epi, class Sched, bool ALIGN_EPI = false, bool SP2 = false>
; __device__ __forceinline__ void gemm_phase(PG8_LAS unsigned char* lds, const Gemm g, const Sched& S, const Epi& E) {
;     ...
;             PG8_LDB(B0, 1, 0); PG8_LDB(B1, 1, 1); PG8_SCHED; PG8_LDA(At, 1, 0); PG8_STAGE(PG8_SA(0, 1), a2 + hstep, voffA);
;             PG8_WAIT_V(8); PG8_WAIT_L(0); PG8_BAR; PG8_MMA(0, 0, At, B0); if (doB1) PG8_MMA(0, 1, At, B1); PG8_BAR; PG8_SCHED;
.LBB0_433:
	s_barrier
	v_add_u32_e32 v128, 0x18000, v247
	ds_read_b128 v[162:165], v128
	ds_read_b128 v[166:169], v128 offset:1024
	ds_read_b128 v[170:173], v128 offset:2048
	ds_read_b128 v[174:177], v128 offset:3072
	v_add_u32_e32 v128, 0x1c000, v247
	ds_read_b128 v[146:149], v128
	ds_read_b128 v[150:153], v128 offset:1024
	ds_read_b128 v[154:157], v128 offset:2048
	ds_read_b128 v[158:161], v128 offset:3072
	s_add_u32 s94, s94, 0x40000
	s_addc_u32 s95, s95, 0
	s_mov_b32 m0, s27
	s_nop 0
	v_lshl_add_u64 v[130:131], s[94:95], 0, v[214:215]
	ds_read_b128 v[202:205], v248 offset:32768
	ds_read_b128 v[206:209], v248 offset:33792
	ds_read_b128 v[194:197], v248 offset:34816
	ds_read_b128 v[198:201], v248 offset:35840
	ds_read_b128 v[186:189], v248 offset:36864
	ds_read_b128 v[190:193], v248 offset:37888
	ds_read_b128 v[178:181], v248 offset:38912
	ds_read_b128 v[182:185], v248 offset:39936
	global_load_lds_dwordx4 v[130:131], off
	v_lshl_add_u64 v[130:131], s[94:95], 0, v[218:219]
	s_mov_b32 m0, s28
	s_nop 0
	global_load_lds_dwordx4 v[130:131], off
	s_waitcnt vmcnt(8)
	s_waitcnt lgkmcnt(0)
	s_barrier
	s_setprio 1
	s_waitcnt lgkmcnt(0)
	v_mfma_f32_16x16x32_bf16 v[96:99], v[162:165], v[202:205], v[96:99]
	v_mfma_f32_16x16x32_bf16 v[142:145], v[166:169], v[206:209], v[96:99]
	v_mfma_f32_16x16x32_bf16 v[96:99], v[170:173], v[202:205], v[100:103]
	v_mfma_f32_16x16x32_bf16 v[138:141], v[174:177], v[206:209], v[96:99]
	v_mfma_f32_16x16x32_bf16 v[96:99], v[162:165], v[194:197], v[104:107]
	v_mfma_f32_16x16x32_bf16 v[134:137], v[166:169], v[198:201], v[96:99]
	v_mfma_f32_16x16x32_bf16 v[96:99], v[170:173], v[194:197], v[108:111]
	v_mfma_f32_16x16x32_bf16 v[130:133], v[174:177], v[198:201], v[96:99]
	v_mfma_f32_16x16x32_bf16 v[96:99], v[162:165], v[186:189], v[116:119]
	v_mfma_f32_16x16x32_bf16 v[116:119], v[166:169], v[190:193], v[96:99]
	v_mfma_f32_16x16x32_bf16 v[96:99], v[170:173], v[186:189], v[112:115]
	v_mfma_f32_16x16x32_bf16 v[92:95], v[162:165], v[178:181], v[92:95]
	v_mfma_f32_16x16x32_bf16 v[88:91], v[170:173], v[178:181], v[88:91]
	v_mfma_f32_16x16x32_bf16 v[112:115], v[174:177], v[190:193], v[96:99]
	v_mfma_f32_16x16x32_bf16 v[92:95], v[166:169], v[182:185], v[92:95]
	v_mfma_f32_16x16x32_bf16 v[88:91], v[174:177], v[182:185], v[88:91]
	s_setprio 0
	s_and_b64 vcc, exec, s[8:9]
	s_cbranch_vccnz .LBB0_435
	s_setprio 1
	v_mfma_f32_16x16x32_bf16 v[96:99], v[146:149], v[202:205], v[124:127]
	v_mfma_f32_16x16x32_bf16 v[124:127], v[150:153], v[206:209], v[96:99]
	v_mfma_f32_16x16x32_bf16 v[96:99], v[154:157], v[202:205], v[120:123]
	v_mfma_f32_16x16x32_bf16 v[84:87], v[146:149], v[194:197], v[84:87]
	v_mfma_f32_16x16x32_bf16 v[80:83], v[154:157], v[194:197], v[80:83]
	v_mfma_f32_16x16x32_bf16 v[76:79], v[146:149], v[186:189], v[76:79]
	v_mfma_f32_16x16x32_bf16 v[72:75], v[154:157], v[186:189], v[72:75]
	v_mfma_f32_16x16x32_bf16 v[68:71], v[146:149], v[178:181], v[68:71]
	v_mfma_f32_16x16x32_bf16 v[64:67], v[154:157], v[178:181], v[64:67]
	v_mfma_f32_16x16x32_bf16 v[120:123], v[158:161], v[206:209], v[96:99]
	v_mfma_f32_16x16x32_bf16 v[84:87], v[150:153], v[198:201], v[84:87]
	v_mfma_f32_16x16x32_bf16 v[80:83], v[158:161], v[198:201], v[80:83]
	v_mfma_f32_16x16x32_bf16 v[76:79], v[150:153], v[190:193], v[76:79]
	v_mfma_f32_16x16x32_bf16 v[72:75], v[158:161], v[190:193], v[72:75]
	v_mfma_f32_16x16x32_bf16 v[68:71], v[150:153], v[182:185], v[68:71]
	v_mfma_f32_16x16x32_bf16 v[64:67], v[158:161], v[182:185], v[64:67]
	s_setprio 0

; #define PG8_STAGE(bufoff, gbase, voff) do { _Pragma("unroll") for (int _i = 0; _i < 2; ++_i) \
;         __builtin_amdgcn_global_load_lds((const unsigned*)((const char*)(gbase) + (voff)[_i]), (PG8_LAS unsigned*)(lds + (bufoff) + ldsw + _i * 8192), 16, 0, 0); } while (0)
; #define PG8_LDA(dst, b, h) do { _Pragma("unroll") for (int m = 0; m < 4; ++m) _Pragma("unroll") for (int k = 0; k < 2; ++k) dst[m][k] = *(const PG8_LAS bf16x8*)(lds + PG8_SA(b, h) + aoff + m * 2048 + k * 1024); } while (0)
; #define PG8_LDB(dst, b, h) do { _Pragma("unroll") for (int n = 0; n < 2; ++n) _Pragma("unroll") for (int k = 0; k < 2; ++k) dst[n][k] = *(const PG8_LAS bf16x8*)(lds + PG8_SB(b, h) + boff + n * 2048 + k * 1024); } while (0)
; #define PG8_MMA(ai, bj, At, Bt) do { __builtin_amdgcn_s_setprio(1); _Pragma("unroll") for (int m = 0; m < 4; ++m) _Pragma("unroll") for (int n = 0; n < 2; ++n) _Pragma("unroll") for (int k = 0; k < 2; ++k) \
;         acc[ai][bj][m][n] = __builtin_amdgcn_mfma_f32_16x16x32_bf16(Bt[n][k], At[m][k], acc[ai][bj][m][n], 0, 0, 0); __builtin_amdgcn_s_setprio(0); } while (0)
; #define PG8_WAIT_V(n) asm volatile("s_waitcnt vmcnt(" #n ")" ::: "memory")
; #define PG8_WAIT_L(n) asm volatile("s_waitcnt lgkmcnt(" #n ")" ::: "memory")
; #define PG8_BAR __builtin_amdgcn_s_barrier()
; #define PG8_SCHED __builtin_amdgcn_sched_barrier(0)
; template <class Epi, class Sched, bool ALIGN_EPI = false, bool SP2 = false>
; __device__ __forceinline__ void gemm_phase(PG8_LAS unsigned char* lds, const Gemm g, const Sched& S, const Epi& E) {
;     ...
;             PG8_LDB(B0, 0, 0); PG8_LDB(B1, 0, 1); PG8_SCHED; PG8_LDA(At, 0, 0); PG8_STAGE(PG8_SA(1, 1), a1 + hstep, voffA);
;             PG8_WAIT_V(8); PG8_WAIT_L(0); PG8_BAR; PG8_MMA(0, 0, At, B0); if (doB1) PG8_MMA(0, 1, At, B1); PG8_BAR; PG8_SCHED;
.LBB0_847:
	v_add_u32_e32 v128, 0x10000, v234
	ds_read_b128 v[146:149], v128
	ds_read_b128 v[150:153], v128 offset:1024
	ds_read_b128 v[154:157], v128 offset:2048
	ds_read_b128 v[158:161], v128 offset:3072
	v_add_u32_e32 v128, 0x14000, v234
	ds_read_b128 v[130:133], v128
	ds_read_b128 v[134:137], v128 offset:1024
	ds_read_b128 v[138:141], v128 offset:2048
	ds_read_b128 v[142:145], v128 offset:3072
	v_lshl_add_u64 v[214:215], s[60:61], 0, v[206:207]
	s_add_i32 m0, s50, 0xc000
	s_nop 0
	ds_read_b128 v[186:189], v235
	ds_read_b128 v[190:193], v235 offset:1024
	ds_read_b128 v[178:181], v235 offset:2048
	ds_read_b128 v[182:185], v235 offset:3072
	ds_read_b128 v[170:173], v235 offset:4096
	ds_read_b128 v[174:177], v235 offset:5120
	ds_read_b128 v[162:165], v235 offset:6144
	ds_read_b128 v[166:169], v235 offset:7168
	global_load_lds_dwordx4 v[214:215], off
	v_lshl_add_u64 v[214:215], s[60:61], 0, v[208:209]
	s_add_i32 m0, s50, 0xe000
	s_nop 0
	global_load_lds_dwordx4 v[214:215], off
	s_waitcnt vmcnt(8)
	s_waitcnt lgkmcnt(0)
	s_barrier
	s_setprio 1
	s_waitcnt lgkmcnt(0)
	v_mfma_f32_16x16x32_bf16 v[124:127], v[146:149], v[186:189], v[124:127]
	v_mfma_f32_16x16x32_bf16 v[120:123], v[154:157], v[186:189], v[120:123]
	v_mfma_f32_16x16x32_bf16 v[116:119], v[146:149], v[178:181], v[116:119]
	v_mfma_f32_16x16x32_bf16 v[112:115], v[154:157], v[178:181], v[112:115]
	v_mfma_f32_16x16x32_bf16 v[92:95], v[146:149], v[170:173], v[92:95]
	v_mfma_f32_16x16x32_bf16 v[88:91], v[154:157], v[170:173], v[88:91]
	v_mfma_f32_16x16x32_bf16 v[84:87], v[146:149], v[162:165], v[84:87]
	v_mfma_f32_16x16x32_bf16 v[80:83], v[154:157], v[162:165], v[80:83]
	v_mfma_f32_16x16x32_bf16 v[124:127], v[150:153], v[190:193], v[124:127]
	v_mfma_f32_16x16x32_bf16 v[120:123], v[158:161], v[190:193], v[120:123]
	v_mfma_f32_16x16x32_bf16 v[116:119], v[150:153], v[182:185], v[116:119]
	v_mfma_f32_16x16x32_bf16 v[112:115], v[158:161], v[182:185], v[112:115]
	v_mfma_f32_16x16x32_bf16 v[92:95], v[150:153], v[174:177], v[92:95]
	v_mfma_f32_16x16x32_bf16 v[88:91], v[158:161], v[174:177], v[88:91]
	v_mfma_f32_16x16x32_bf16 v[84:87], v[150:153], v[166:169], v[84:87]
	v_mfma_f32_16x16x32_bf16 v[80:83], v[158:161], v[166:169], v[80:83]
	s_setprio 0
	v_cndmask_b32_e64 v128, 0, 1, s[72:73]
	v_cmp_ne_u32_e64 s[8:9], 1, v128
	s_andn2_b64 vcc, exec, s[72:73]
	s_cbranch_vccnz .LBB0_849
	s_setprio 1
	v_mfma_f32_16x16x32_bf16 v[108:111], v[130:133], v[186:189], v[108:111]
	v_mfma_f32_16x16x32_bf16 v[104:107], v[138:141], v[186:189], v[104:107]
	v_mfma_f32_16x16x32_bf16 v[100:103], v[130:133], v[178:181], v[100:103]
	v_mfma_f32_16x16x32_bf16 v[96:99], v[138:141], v[178:181], v[96:99]
	v_mfma_f32_16x16x32_bf16 v[76:79], v[130:133], v[170:173], v[76:79]
	v_mfma_f32_16x16x32_bf16 v[72:75], v[138:141], v[170:173], v[72:75]
	v_mfma_f32_16x16x32_bf16 v[68:71], v[130:133], v[162:165], v[68:71]
	v_mfma_f32_16x16x32_bf16 v[64:67], v[138:141], v[162:165], v[64:67]
	v_mfma_f32_16x16x32_bf16 v[108:111], v[134:137], v[190:193], v[108:111]
	v_mfma_f32_16x16x32_bf16 v[104:107], v[142:145], v[190:193], v[104:107]
	v_mfma_f32_16x16x32_bf16 v[100:103], v[134:137], v[182:185], v[100:103]
	v_mfma_f32_16x16x32_bf16 v[96:99], v[142:145], v[182:185], v[96:99]
	v_mfma_f32_16x16x32_bf16 v[76:79], v[134:137], v[174:177], v[76:79]
	v_mfma_f32_16x16x32_bf16 v[72:75], v[142:145], v[174:177], v[72:75]
	v_mfma_f32_16x16x32_bf16 v[68:71], v[134:137], v[166:169], v[68:71]
	v_mfma_f32_16x16x32_bf16 v[64:67], v[142:145], v[166:169], v[64:67]
	s_setprio 0

; #define PG8_STAGE(bufoff, gbase, voff) do { _Pragma("unroll") for (int _i = 0; _i < 2; ++_i) \
;         __builtin_amdgcn_global_load_lds((const unsigned*)((const char*)(gbase) + (voff)[_i]), (PG8_LAS unsigned*)(lds + (bufoff) + ldsw + _i * 8192), 16, 0, 0); } while (0)
; #define PG8_LDA(dst, b, h) do { _Pragma("unroll") for (int m = 0; m < 4; ++m) _Pragma("unroll") for (int k = 0; k < 2; ++k) dst[m][k] = *(const PG8_LAS bf16x8*)(lds + PG8_SA(b, h) + aoff + m * 2048 + k * 1024); } while (0)
; #define PG8_LDB(dst, b, h) do { _Pragma("unroll") for (int n = 0; n < 2; ++n) _Pragma("unroll") for (int k = 0; k < 2; ++k) dst[n][k] = *(const PG8_LAS bf16x8*)(lds + PG8_SB(b, h) + boff + n * 2048 + k * 1024); } while (0)
; #define PG8_MMA(ai, bj, At, Bt) do { __builtin_amdgcn_s_setprio(1); _Pragma("unroll") for (int m = 0; m < 4; ++m) _Pragma("unroll") for (int n = 0; n < 2; ++n) _Pragma("unroll") for (int k = 0; k < 2; ++k) \
;         acc[ai][bj][m][n] = __builtin_amdgcn_mfma_f32_16x16x32_bf16(Bt[n][k], At[m][k], acc[ai][bj][m][n], 0, 0, 0); __builtin_amdgcn_s_setprio(0); } while (0)
; #define PG8_WAIT_V(n) asm volatile("s_waitcnt vmcnt(" #n ")" ::: "memory")
; #define PG8_WAIT_L(n) asm volatile("s_waitcnt lgkmcnt(" #n ")" ::: "memory")
; #define PG8_BAR __builtin_amdgcn_s_barrier()
; #define PG8_SCHED __builtin_amdgcn_sched_barrier(0)
; template <class Epi, class Sched, bool ALIGN_EPI = false, bool SP2 = false>
; __device__ __forceinline__ void gemm_phase(PG8_LAS unsigned char* lds, const Gemm g, const Sched& S, const Epi& E) {
;     ...
;             PG8_LDB(B0, 1, 0); PG8_LDB(B1, 1, 1); PG8_SCHED; PG8_LDA(At, 1, 0); PG8_STAGE(PG8_SA(0, 1), a2 + hstep, voffA);
;             PG8_WAIT_V(8); PG8_WAIT_L(0); PG8_BAR; PG8_MMA(0, 0, At, B0); if (doB1) PG8_MMA(0, 1, At, B1); PG8_BAR; PG8_SCHED;
.LBB0_852:
	s_barrier
	v_add_u32_e32 v128, 0x18000, v234
	ds_read_b128 v[146:149], v128
	ds_read_b128 v[150:153], v128 offset:1024
	ds_read_b128 v[154:157], v128 offset:2048
	ds_read_b128 v[158:161], v128 offset:3072
	v_add_u32_e32 v128, 0x1c000, v234
	ds_read_b128 v[130:133], v128
	ds_read_b128 v[134:137], v128 offset:1024
	ds_read_b128 v[138:141], v128 offset:2048
	ds_read_b128 v[142:145], v128 offset:3072
	s_add_u32 s74, s74, s88
	s_addc_u32 s75, s75, 0
	s_mov_b32 m0, s71
	v_lshl_add_u64 v[240:241], s[74:75], 0, v[194:195]
	s_nop 0
	ds_read_b128 v[186:189], v235 offset:32768
	ds_read_b128 v[190:193], v235 offset:33792
	ds_read_b128 v[178:181], v235 offset:34816
	ds_read_b128 v[182:185], v235 offset:35840
	ds_read_b128 v[170:173], v235 offset:36864
	ds_read_b128 v[174:177], v235 offset:37888
	ds_read_b128 v[162:165], v235 offset:38912
	ds_read_b128 v[166:169], v235 offset:39936
	global_load_lds_dwordx4 v[240:241], off
	v_lshl_add_u64 v[240:241], s[74:75], 0, v[198:199]
	s_mov_b32 m0, s33
	s_nop 0
	global_load_lds_dwordx4 v[240:241], off
	s_waitcnt vmcnt(8)
	s_waitcnt lgkmcnt(0)
	s_barrier
	s_setprio 1
	s_waitcnt lgkmcnt(0)
	v_mfma_f32_16x16x32_bf16 v[124:127], v[146:149], v[186:189], v[124:127]
	v_mfma_f32_16x16x32_bf16 v[120:123], v[154:157], v[186:189], v[120:123]
	v_mfma_f32_16x16x32_bf16 v[116:119], v[146:149], v[178:181], v[116:119]
	v_mfma_f32_16x16x32_bf16 v[112:115], v[154:157], v[178:181], v[112:115]
	v_mfma_f32_16x16x32_bf16 v[92:95], v[146:149], v[170:173], v[92:95]
	v_mfma_f32_16x16x32_bf16 v[88:91], v[154:157], v[170:173], v[88:91]
	v_mfma_f32_16x16x32_bf16 v[84:87], v[146:149], v[162:165], v[84:87]
	v_mfma_f32_16x16x32_bf16 v[80:83], v[154:157], v[162:165], v[80:83]
	v_mfma_f32_16x16x32_bf16 v[124:127], v[150:153], v[190:193], v[124:127]
	v_mfma_f32_16x16x32_bf16 v[120:123], v[158:161], v[190:193], v[120:123]
	v_mfma_f32_16x16x32_bf16 v[116:119], v[150:153], v[182:185], v[116:119]
	v_mfma_f32_16x16x32_bf16 v[112:115], v[158:161], v[182:185], v[112:115]
	v_mfma_f32_16x16x32_bf16 v[92:95], v[150:153], v[174:177], v[92:95]
	v_mfma_f32_16x16x32_bf16 v[88:91], v[158:161], v[174:177], v[88:91]
	v_mfma_f32_16x16x32_bf16 v[84:87], v[150:153], v[166:169], v[84:87]
	v_mfma_f32_16x16x32_bf16 v[80:83], v[158:161], v[166:169], v[80:83]
	s_setprio 0
	s_and_b64 vcc, exec, s[8:9]
	s_cbranch_vccnz .LBB0_854
	s_setprio 1
	v_mfma_f32_16x16x32_bf16 v[108:111], v[130:133], v[186:189], v[108:111]
	v_mfma_f32_16x16x32_bf16 v[104:107], v[138:141], v[186:189], v[104:107]
	v_mfma_f32_16x16x32_bf16 v[100:103], v[130:133], v[178:181], v[100:103]
	v_mfma_f32_16x16x32_bf16 v[96:99], v[138:141], v[178:181], v[96:99]
	v_mfma_f32_16x16x32_bf16 v[76:79], v[130:133], v[170:173], v[76:79]
	v_mfma_f32_16x16x32_bf16 v[72:75], v[138:141], v[170:173], v[72:75]
	v_mfma_f32_16x16x32_bf16 v[68:71], v[130:133], v[162:165], v[68:71]
	v_mfma_f32_16x16x32_bf16 v[64:67], v[138:141], v[162:165], v[64:67]
	v_mfma_f32_16x16x32_bf16 v[108:111], v[134:137], v[190:193], v[108:111]
	v_mfma_f32_16x16x32_bf16 v[104:107], v[142:145], v[190:193], v[104:107]
	v_mfma_f32_16x16x32_bf16 v[100:103], v[134:137], v[182:185], v[100:103]
	v_mfma_f32_16x16x32_bf16 v[96:99], v[142:145], v[182:185], v[96:99]
	v_mfma_f32_16x16x32_bf16 v[76:79], v[134:137], v[174:177], v[76:79]
	v_mfma_f32_16x16x32_bf16 v[72:75], v[142:145], v[174:177], v[72:75]
	v_mfma_f32_16x16x32_bf16 v[68:71], v[134:137], v[166:169], v[68:71]
	v_mfma_f32_16x16x32_bf16 v[64:67], v[142:145], v[166:169], v[64:67]
	s_setprio 0
